# attention: waves whose tile starts at their first query skip the fully masked upper 32 keys (4 QK MFMAs, 16 exps, chains and 4 PV MFMAs); results bit-identical
# baseline (speedup 1.0000x reference)
; #define LAS __attribute__((address_space(3)))
;     ...
;         if (k0 < qw + 32 && alive) {
;             const LAS unsigned char* kb = lds + AT_K + cur * 8192 + hi * 1024 + r32 * 16;
;             f32x16 p0, p1;
; #pragma unroll
;             for (int r = 0; r < 16; ++r) { p0[r] = 0.f; p1[r] = 0.f; }
; #pragma unroll
;             for (int d0 = 0; d0 < 4; ++d0) {
;                 const bf16x8 a0 = *(const LAS bf16x8*)(kb + d0 * 2048), a1 = *(const LAS bf16x8*)(kb + d0 * 2048 + 512);
;                 p0 = __builtin_amdgcn_mfma_f32_32x32x16_bf16(a0, qr[d0], p0, 0, 0, 0);
;                 p1 = __builtin_amdgcn_mfma_f32_32x32x16_bf16(a1, qr[d0], p1, 0, 0, 0);
;             }
; #pragma unroll
;             for (int r = 0; r < 16; ++r) { p0[r] = __builtin_amdgcn_rcpf(1.f + __builtin_amdgcn_exp2f(p0[r])); p1[r] = __builtin_amdgcn_rcpf(1.f + __builtin_amdgcn_exp2f(p1[r])); }
;             if (k0 + 63 >= qw) {
;                 const int kb0 = k0 + 16 * hi;
; #pragma unroll
;                 for (int r = 0; r < 16; ++r) { if (kb0 + r >= qrel) p0[r] = 1.f; if (kb0 + 32 + r >= qrel) p1[r] = 1.f; }
;             }
.LBB0_461:
	s_and_b32 s1, s6, 1
	s_cmp_le_i32 s27, s24
	s_cselect_b64 s[4:5], -1, 0
	v_cmp_ne_u32_e32 vcc, 0, v32
	s_and_b64 s[4:5], s[4:5], vcc
	s_andn2_b64 vcc, exec, s[4:5]
	s_cbranch_vccnz .LBB0_471
	s_cmp_eq_u32 s27, s24
	s_cbranch_scc1 .Lattn_half_path
	v_lshl_add_u32 v94, s1, 13, v111
	s_mul_i32 s98, s1, 0x2400
	ds_read_b128 v[156:159], v94
	ds_read_b128 v[160:163], v94 offset:2048
	ds_read_b128 v[168:171], v94 offset:4096
	ds_read_b128 v[172:175], v94 offset:6144
	ds_read_b128 v[176:179], v94 offset:512
	ds_read_b128 v[180:183], v94 offset:2560
	ds_read_b128 v[184:187], v94 offset:4608
	ds_read_b128 v[188:191], v94 offset:6656
	v_add_u32_e32 v126, s98, v112
	s_add_i32 s4, s27, 63
	s_cmp_lt_i32 s4, s24
	s_waitcnt lgkmcnt(7)
	v_mfma_f32_32x32x16_bf16 v[32:47], v[156:159], v[66:69], 0
	ds_read_b128 v[206:209], v126 offset:16384
	s_waitcnt lgkmcnt(7)
	v_mfma_f32_32x32x16_bf16 v[32:47], v[160:163], v[70:73], v[32:47]
	ds_read_b128 v[210:213], v126 offset:20992
	s_waitcnt lgkmcnt(7)
	v_mfma_f32_32x32x16_bf16 v[32:47], v[168:171], v[74:77], v[32:47]
	ds_read_b128 v[214:217], v126 offset:16400
	s_waitcnt lgkmcnt(7)
	v_mfma_f32_32x32x16_bf16 v[32:47], v[172:175], v[78:81], v[32:47]
	ds_read_b128 v[218:221], v126 offset:21008
	s_waitcnt lgkmcnt(7)
	v_mfma_f32_32x32x16_bf16 v[48:63], v[176:179], v[66:69], 0
	ds_read_b128 v[222:225], v126 offset:16448
	s_waitcnt lgkmcnt(7)
	v_mfma_f32_32x32x16_bf16 v[48:63], v[180:183], v[70:73], v[48:63]
	ds_read_b128 v[226:229], v126 offset:21056
	s_waitcnt lgkmcnt(7)
	v_mfma_f32_32x32x16_bf16 v[48:63], v[184:187], v[74:77], v[48:63]
	ds_read_b128 v[118:121], v126 offset:16464
	s_waitcnt lgkmcnt(7)
	v_mfma_f32_32x32x16_bf16 v[48:63], v[188:191], v[78:81], v[48:63]
	ds_read_b128 v[122:125], v126 offset:21072
	v_exp_f32_e32 v32, v32
	v_exp_f32_e32 v33, v33
	v_exp_f32_e32 v34, v34
	v_exp_f32_e32 v35, v35
	v_exp_f32_e32 v36, v36
	v_exp_f32_e32 v37, v37
	v_exp_f32_e32 v38, v38
	v_exp_f32_e32 v39, v39
	v_exp_f32_e32 v40, v40
	v_exp_f32_e32 v41, v41
	v_exp_f32_e32 v42, v42
	v_exp_f32_e32 v43, v43
	v_exp_f32_e32 v44, v44
	v_exp_f32_e32 v45, v45
	v_exp_f32_e32 v46, v46
	v_exp_f32_e32 v47, v47
	v_exp_f32_e32 v48, v48
	v_exp_f32_e32 v49, v49
	v_exp_f32_e32 v50, v50
	v_exp_f32_e32 v51, v51
	v_exp_f32_e32 v52, v52
	v_exp_f32_e32 v53, v53
	v_exp_f32_e32 v54, v54
	v_exp_f32_e32 v55, v55
	v_exp_f32_e32 v56, v56
	v_exp_f32_e32 v57, v57
	v_exp_f32_e32 v58, v58
	v_exp_f32_e32 v59, v59
	v_exp_f32_e32 v60, v60
	v_exp_f32_e32 v61, v61
	v_exp_f32_e32 v62, v62
	v_exp_f32_e32 v63, v63
	s_cbranch_scc1 .Lattn_nomask
	v_sub_u32_e32 v230, v109, v64
	v_subrev_u32_e32 v230, s27, v230
	v_cmp_gt_i32_e64 s[42:43], v230, 0
	v_cmp_gt_i32_e64 s[44:45], v230, 1
	v_cmp_gt_i32_e64 s[46:47], v230, 2
	v_cmp_gt_i32_e64 s[48:49], v230, 3
	v_cndmask_b32_e64 v32, 0, v32, s[42:43]
	v_cndmask_b32_e64 v33, 0, v33, s[44:45]
	v_cndmask_b32_e64 v34, 0, v34, s[46:47]
	v_cndmask_b32_e64 v35, 0, v35, s[48:49]
	v_cmp_gt_i32_e64 s[42:43], v230, 4
	v_cmp_gt_i32_e64 s[44:45], v230, 5
	v_cmp_gt_i32_e64 s[46:47], v230, 6
	v_cmp_gt_i32_e64 s[48:49], v230, 7
	v_cndmask_b32_e64 v36, 0, v36, s[42:43]
	v_cndmask_b32_e64 v37, 0, v37, s[44:45]
	v_cndmask_b32_e64 v38, 0, v38, s[46:47]
	v_cndmask_b32_e64 v39, 0, v39, s[48:49]
	v_cmp_gt_i32_e64 s[42:43], v230, 8
	v_cmp_gt_i32_e64 s[44:45], v230, 9
	v_cmp_gt_i32_e64 s[46:47], v230, 10
	v_cmp_gt_i32_e64 s[48:49], v230, 11
	v_cndmask_b32_e64 v40, 0, v40, s[42:43]
	v_cndmask_b32_e64 v41, 0, v41, s[44:45]
	v_cndmask_b32_e64 v42, 0, v42, s[46:47]
	v_cndmask_b32_e64 v43, 0, v43, s[48:49]
	v_cmp_gt_i32_e64 s[42:43], v230, 12
	v_cmp_gt_i32_e64 s[44:45], v230, 13
	v_cmp_gt_i32_e64 s[46:47], v230, 14
	v_cmp_gt_i32_e64 s[48:49], v230, 15
	v_cndmask_b32_e64 v44, 0, v44, s[42:43]
	v_cndmask_b32_e64 v45, 0, v45, s[44:45]
	v_cndmask_b32_e64 v46, 0, v46, s[46:47]
	v_cndmask_b32_e64 v47, 0, v47, s[48:49]
	v_cmp_gt_i32_e64 s[42:43], v230, 32
	v_cmp_gt_i32_e64 s[44:45], v230, 33
	v_cmp_gt_i32_e64 s[46:47], v230, 34
	v_cmp_gt_i32_e64 s[48:49], v230, 35
	v_cndmask_b32_e64 v48, 0, v48, s[42:43]
	v_cndmask_b32_e64 v49, 0, v49, s[44:45]
	v_cndmask_b32_e64 v50, 0, v50, s[46:47]
	v_cndmask_b32_e64 v51, 0, v51, s[48:49]
	v_cmp_gt_i32_e64 s[42:43], v230, 36
	v_cmp_gt_i32_e64 s[44:45], v230, 37
	v_cmp_gt_i32_e64 s[46:47], v230, 38
	v_cmp_gt_i32_e64 s[48:49], v230, 39
	v_cndmask_b32_e64 v52, 0, v52, s[42:43]
	v_cndmask_b32_e64 v53, 0, v53, s[44:45]
	v_cndmask_b32_e64 v54, 0, v54, s[46:47]
	v_cndmask_b32_e64 v55, 0, v55, s[48:49]
	v_cmp_gt_i32_e64 s[42:43], v230, 40
	v_cmp_gt_i32_e64 s[44:45], v230, 41
	v_cmp_gt_i32_e64 s[46:47], v230, 42
	v_cmp_gt_i32_e64 s[48:49], v230, 43
	v_cndmask_b32_e64 v56, 0, v56, s[42:43]
	v_cndmask_b32_e64 v57, 0, v57, s[44:45]
	v_cndmask_b32_e64 v58, 0, v58, s[46:47]
	v_cndmask_b32_e64 v59, 0, v59, s[48:49]
	v_cmp_gt_i32_e64 s[42:43], v230, 44
	v_cmp_gt_i32_e64 s[44:45], v230, 45
	v_cmp_gt_i32_e64 s[46:47], v230, 46
	v_cmp_gt_i32_e64 s[48:49], v230, 47
	v_cndmask_b32_e64 v60, 0, v60, s[42:43]
	v_cndmask_b32_e64 v61, 0, v61, s[44:45]
	v_cndmask_b32_e64 v62, 0, v62, s[46:47]
	v_cndmask_b32_e64 v63, 0, v63, s[48:49]

;     ...
;             alive = __any(C != 0.f);
;         }
;         if (it + 1 < NT) AT_WRITE(cur ^ 1);
;         if (lane == 0) aflag[(it & 1) * 8 + wid] = (unsigned)alive;
.Lattn_tail:
	v_cndmask_b32_e64 v32, 0, 1, s[4:5]
	s_andn2_b64 vcc, exec, s[12:13]
	s_cbranch_vccz .LBB0_472

;     ...
;             const LAS unsigned char* kb = lds + AT_K + cur * 8192 + hi * 1024 + r32 * 16;
;             f32x16 p0, p1;
; #pragma unroll
;             for (int r = 0; r < 16; ++r) { p0[r] = 0.f; p1[r] = 0.f; }
; #pragma unroll
;             for (int d0 = 0; d0 < 4; ++d0) {
;                 const bf16x8 a0 = *(const LAS bf16x8*)(kb + d0 * 2048), a1 = *(const LAS bf16x8*)(kb + d0 * 2048 + 512);
;                 p0 = __builtin_amdgcn_mfma_f32_32x32x16_bf16(a0, qr[d0], p0, 0, 0, 0);
;                 p1 = __builtin_amdgcn_mfma_f32_32x32x16_bf16(a1, qr[d0], p1, 0, 0, 0);
;             }
; #pragma unroll
;             for (int r = 0; r < 16; ++r) { p0[r] = __builtin_amdgcn_rcpf(1.f + __builtin_amdgcn_exp2f(p0[r])); p1[r] = __builtin_amdgcn_rcpf(1.f + __builtin_amdgcn_exp2f(p1[r])); }
;             if (k0 + 63 >= qw) {
;                 const int kb0 = k0 + 16 * hi;
; #pragma unroll
;                 for (int r = 0; r < 16; ++r) { if (kb0 + r >= qrel) p0[r] = 1.f; if (kb0 + 32 + r >= qrel) p1[r] = 1.f; }
;             }
; #pragma unroll
;             for (int r = 14; r >= 0; --r) { p0[r] *= p0[r + 1]; p1[r] *= p1[r + 1]; }
;             const float L0 = p0[0], L1 = p1[0];
;             const float pL0 = __shfl_xor(L0, 32), pL1 = __shfl_xor(L1, 32);
;             const float tot1 = L1 * pL1;
;             const float pre1 = hi ? C : C * pL1;
;             const float pre0 = C * tot1 * (hi ? 1.f : pL0);
;             C = C * tot1 * (L0 * pL0);
; #pragma unroll
;             for (int r = 0; r < 15; ++r) { p0[r] = pre0 * (p0[r + 1] - p0[r]); p1[r] = pre1 * (p1[r + 1] - p1[r]); }
;             p0[15] = pre0 * (1.f - p0[15]); p1[15] = pre1 * (1.f - p1[15]);
;             u32x4 w00, w01, w10, w11;
;             w00.x = pk2(p0[0], p0[1]); w00.y = pk2(p0[2], p0[3]); w00.z = pk2(p0[4], p0[5]); w00.w = pk2(p0[6], p0[7]);
;             w01.x = pk2(p0[8], p0[9]); w01.y = pk2(p0[10], p0[11]); w01.z = pk2(p0[12], p0[13]); w01.w = pk2(p0[14], p0[15]);
;             w10.x = pk2(p1[0], p1[1]); w10.y = pk2(p1[2], p1[3]); w10.z = pk2(p1[4], p1[5]); w10.w = pk2(p1[6], p1[7]);
;             w11.x = pk2(p1[8], p1[9]); w11.y = pk2(p1[10], p1[11]); w11.z = pk2(p1[12], p1[13]); w11.w = pk2(p1[14], p1[15]);
;             const LAS unsigned char* vb = lds + AT_V + cur * 9216 + r32 * 144 + hi * 32;
;     ...
;             AT_PV(w00, 0); AT_PV(w01, 16); AT_PV(w10, 64); AT_PV(w11, 80);
.Lattn_half_path:
	v_lshl_add_u32 v94, s1, 13, v111
	s_mul_i32 s98, s1, 0x2400
	ds_read_b128 v[176:179], v94
	ds_read_b128 v[180:183], v94 offset:2048
	ds_read_b128 v[184:187], v94 offset:4096
	ds_read_b128 v[188:191], v94 offset:6144
	v_add_u32_e32 v126, s98, v112
	ds_read_b128 v[206:209], v126 offset:16384
	ds_read_b128 v[210:213], v126 offset:20992
	ds_read_b128 v[214:217], v126 offset:16400
	ds_read_b128 v[218:221], v126 offset:21008
	s_waitcnt lgkmcnt(7)
	v_mfma_f32_32x32x16_bf16 v[32:47], v[176:179], v[66:69], 0
	s_waitcnt lgkmcnt(6)
	v_mfma_f32_32x32x16_bf16 v[32:47], v[180:183], v[70:73], v[32:47]
	s_waitcnt lgkmcnt(5)
	v_mfma_f32_32x32x16_bf16 v[32:47], v[184:187], v[74:77], v[32:47]
	s_waitcnt lgkmcnt(4)
	v_mfma_f32_32x32x16_bf16 v[32:47], v[188:191], v[78:81], v[32:47]
	v_sub_u32_e32 v230, v109, v64
	v_subrev_u32_e32 v230, s27, v230
	s_nop 11
	v_exp_f32_e32 v32, v32
	v_exp_f32_e32 v33, v33
	v_exp_f32_e32 v34, v34
	v_exp_f32_e32 v35, v35
	v_exp_f32_e32 v36, v36
	v_exp_f32_e32 v37, v37
	v_exp_f32_e32 v38, v38
	v_exp_f32_e32 v39, v39
	v_exp_f32_e32 v40, v40
	v_exp_f32_e32 v41, v41
	v_exp_f32_e32 v42, v42
	v_exp_f32_e32 v43, v43
	v_exp_f32_e32 v44, v44
	v_exp_f32_e32 v45, v45
	v_exp_f32_e32 v46, v46
	v_exp_f32_e32 v47, v47
	v_cmp_gt_i32_e64 s[42:43], v230, 0
	v_cmp_gt_i32_e64 s[44:45], v230, 1
	v_cmp_gt_i32_e64 s[46:47], v230, 2
	v_cmp_gt_i32_e64 s[48:49], v230, 3
	v_cndmask_b32_e64 v32, 0, v32, s[42:43]
	v_cndmask_b32_e64 v33, 0, v33, s[44:45]
	v_cndmask_b32_e64 v34, 0, v34, s[46:47]
	v_cndmask_b32_e64 v35, 0, v35, s[48:49]
	v_cmp_gt_i32_e64 s[42:43], v230, 4
	v_cmp_gt_i32_e64 s[44:45], v230, 5
	v_cmp_gt_i32_e64 s[46:47], v230, 6
	v_cmp_gt_i32_e64 s[48:49], v230, 7
	v_cndmask_b32_e64 v36, 0, v36, s[42:43]
	v_cndmask_b32_e64 v37, 0, v37, s[44:45]
	v_cndmask_b32_e64 v38, 0, v38, s[46:47]
	v_cndmask_b32_e64 v39, 0, v39, s[48:49]
	v_cmp_gt_i32_e64 s[42:43], v230, 8
	v_cmp_gt_i32_e64 s[44:45], v230, 9
	v_cmp_gt_i32_e64 s[46:47], v230, 10
	v_cmp_gt_i32_e64 s[48:49], v230, 11
	v_cndmask_b32_e64 v40, 0, v40, s[42:43]
	v_cndmask_b32_e64 v41, 0, v41, s[44:45]
	v_cndmask_b32_e64 v42, 0, v42, s[46:47]
	v_cndmask_b32_e64 v43, 0, v43, s[48:49]
	v_cmp_gt_i32_e64 s[42:43], v230, 12
	v_cmp_gt_i32_e64 s[44:45], v230, 13
	v_cmp_gt_i32_e64 s[46:47], v230, 14
	v_cmp_gt_i32_e64 s[48:49], v230, 15
	v_cndmask_b32_e64 v44, 0, v44, s[42:43]
	v_cndmask_b32_e64 v45, 0, v45, s[44:45]
	v_cndmask_b32_e64 v46, 0, v46, s[46:47]
	v_cndmask_b32_e64 v47, 0, v47, s[48:49]
	v_add_f32_e32 v156, 1.0, v32
	v_add_f32_e32 v168, 1.0, v40
	v_mul_f32_e32 v33, v156, v33
	v_mul_f32_e32 v41, v168, v41
	v_add_f32_e32 v157, v156, v33
	v_add_f32_e32 v169, v168, v41
	v_mul_f32_e32 v34, v157, v34
	v_mul_f32_e32 v42, v169, v42
	v_add_f32_e32 v158, v157, v34
	v_add_f32_e32 v170, v169, v42
	v_mul_f32_e32 v35, v158, v35
	v_mul_f32_e32 v43, v170, v43
	v_add_f32_e32 v159, v158, v35
	v_add_f32_e32 v171, v170, v43
	v_mul_f32_e32 v36, v159, v36
	v_mul_f32_e32 v44, v171, v44
	v_add_f32_e32 v160, v159, v36
	v_add_f32_e32 v172, v171, v44
	v_mul_f32_e32 v37, v160, v37
	v_mul_f32_e32 v45, v172, v45
	v_add_f32_e32 v161, v160, v37
	v_add_f32_e32 v173, v172, v45
	v_mul_f32_e32 v38, v161, v38
	v_mul_f32_e32 v46, v173, v46
	v_add_f32_e32 v162, v161, v38
	v_add_f32_e32 v174, v173, v46
	v_mul_f32_e32 v39, v162, v39
	v_mul_f32_e32 v47, v174, v47
	v_add_f32_e32 v163, v162, v39
	v_add_f32_e32 v175, v174, v47
	v_rcp_f32_e32 v246, v163
	v_rcp_f32_e32 v247, v175
	s_nop 1
	v_mul_f32_e32 v250, v246, v247
	v_mul_f32_e32 v230, v246, v247
	s_nop 1
	v_permlane32_swap_b32_e32 v250, v230
	s_nop 1
	v_cndmask_b32_e64 v239, 1.0, v230, s[36:37]
	v_mul_f32_e32 v230, v250, v230
	v_mul_f32_e32 v239, v95, v239
	v_mul_f32_e32 v95, v95, v230
	v_mul_f32_e32 v239, v239, v247
	v_cmp_neq_f32_e32 vcc, 0, v95
	v_mul_f32_e32 v237, v239, v246
	s_cmp_lg_u64 vcc, 0
	s_cselect_b64 s[4:5], -1, 0
	v_mul_f32_e32 v32, v237, v32
	v_mul_f32_e32 v33, v237, v33
	v_mul_f32_e32 v34, v237, v34
	v_mul_f32_e32 v35, v237, v35
	v_mul_f32_e32 v36, v237, v36
	v_mul_f32_e32 v37, v237, v37
	v_mul_f32_e32 v38, v237, v38
	v_mul_f32_e32 v39, v237, v39
	v_mul_f32_e32 v40, v239, v40
	v_mul_f32_e32 v41, v239, v41
	v_mul_f32_e32 v42, v239, v42
	v_mul_f32_e32 v43, v239, v43
	v_mul_f32_e32 v44, v239, v44
	v_mul_f32_e32 v45, v239, v45
	v_mul_f32_e32 v46, v239, v46
	v_mul_f32_e32 v47, v239, v47
	v_cvt_pk_bf16_f32 v142, v32, v33
	v_cvt_pk_bf16_f32 v143, v34, v35
	v_cvt_pk_bf16_f32 v144, v36, v37
	v_cvt_pk_bf16_f32 v145, v38, v39
	v_cvt_pk_bf16_f32 v146, v40, v41
	v_cvt_pk_bf16_f32 v147, v42, v43
	v_cvt_pk_bf16_f32 v148, v44, v45
	v_cvt_pk_bf16_f32 v149, v46, v47
	s_waitcnt lgkmcnt(0)
	v_mfma_f32_32x32x16_bf16 v[16:31], v[206:209], v[142:145], v[16:31]
	v_mfma_f32_32x32x16_bf16 v[0:15], v[210:213], v[142:145], v[0:15]
	v_mfma_f32_32x32x16_bf16 v[16:31], v[214:217], v[146:149], v[16:31]
	v_mfma_f32_32x32x16_bf16 v[0:15], v[218:221], v[146:149], v[0:15]
	s_branch .Lattn_tail
